# baseline (speedup 1.0000x reference)
; template <int EPI, int AMAP, int KOFFMODE, int K>
; __device__ __forceinline__ void gemm_phase(unsigned char* smem, const bf16_t* A, int lda, const bf16_t* Bt, int NT, const EpiArgs& ea) {
;     ...
;         for (int kt = 0; kt < nk; ++kt) {
;             if (kt + 1 < nk) GEMM_DMA(m0, n0, kt + 1, cur ^ 1);
;             else if (have_next) GEMM_DMA(m0n, n0n, 0, cur ^ 1);
;             const unsigned char* Ac = smem + cur * STGB + (wm * 128 + l31) * 128;
;             const unsigned char* Bc = smem + cur * STGB + 32768 + (wn * 64 + l31) * 128;
;             bf16x8 fa[2][4], fb[2][2];
;             fb[0][0] = *(const bf16x8*)(Bc + (((0) ^ yz) & 7) * 16);
;             fb[0][1] = *(const bf16x8*)(Bc + 32 * 128 + (((0) ^ yz) & 7) * 16);
; #pragma unroll
;             for (int i = 0; i < 4; ++i) fa[0][i] = *(const bf16x8*)(Ac + i * 32 * 128 + (((0) ^ yz) & 7) * 16);
; #pragma unroll
;             for (int s = 0; s < 4; ++s) {
;                 if (s < 3) {
;                     const int o_ = (((2 * (s + 1)) ^ yz) & 7) * 16;
;                     fb[(s + 1) & 1][0] = *(const bf16x8*)(Bc + o_);
;                     fb[(s + 1) & 1][1] = *(const bf16x8*)(Bc + 32 * 128 + o_);
; #pragma unroll
;                     for (int i = 0; i < 4; ++i) fa[(s + 1) & 1][i] = *(const bf16x8*)(Ac + i * 32 * 128 + o_);
;                 }
; #pragma unroll
;                 for (int i = 0; i < 4; ++i) {
;                     acc[i][0] = __builtin_amdgcn_mfma_f32_32x32x16_bf16(fa[s & 1][i], fb[s & 1][0], acc[i][0], 0, 0, 0);
;                     acc[i][1] = __builtin_amdgcn_mfma_f32_32x32x16_bf16(fa[s & 1][i], fb[s & 1][1], acc[i][1], 0, 0, 0);
;                 }
;                 __builtin_amdgcn_sched_barrier(0);
;             }
;             if (kt + 1 < nk) asm volatile("s_waitcnt vmcnt(0)" ::: "memory");
;             __builtin_amdgcn_s_barrier();
.LBB0_155:
	s_mov_b32 s9, s13
	s_lshl_b32 s13, s9, 16
	s_xor_b32 s12, s13, 0x10000
	v_readfirstlane_b32 s14, v142
	s_nop 0
	s_add_u32 s14, s14, s12
	v_add3_u32 v162, s13, v149, v147
	v_add_u32_e32 v162, v162, v151
	ds_read_b128 v[162:165], v162 offset:32768
	v_add3_u32 v208, s13, v149, v147
	v_add_u32_e32 v208, v208, v151
	ds_read_b128 v[208:211], v208 offset:36864
	s_waitcnt lgkmcnt(5)
	v_mfma_f32_32x32x16_bf16 v[114:129], v[192:195], v[154:157], v[114:129]
	v_mfma_f32_32x32x16_bf16 v[98:113], v[192:195], v[158:161], v[98:113]
	s_mov_b32 m0, s14
	v_lshl_add_u64 v[192:193], v[136:137], 0, s[4:5]
	v_lshl_add_u64 v[192:193], v[192:193], 0, s[20:21]
	global_load_lds_dwordx4 v[192:193], off
	s_add_u32 m0, s14, 0x2000
	v_lshl_add_u64 v[192:193], v[136:137], 0, s[4:5]
	v_lshl_add_u64 v[192:193], v[192:193], 0, s[80:81]
	global_load_lds_dwordx4 v[192:193], off
	s_add_u32 m0, s14, 0x4000
	v_lshl_add_u64 v[192:193], v[136:137], 0, s[4:5]
	v_lshl_add_u64 v[192:193], v[192:193], 0, s[88:89]
	global_load_lds_dwordx4 v[192:193], off
	s_add_u32 m0, s14, 0x6000
	v_lshl_add_u64 v[192:193], v[136:137], 0, s[4:5]
	v_lshl_add_u64 v[192:193], v[192:193], 0, s[62:63]
	global_load_lds_dwordx4 v[192:193], off
	s_add_u32 m0, s14, 0x8000
	v_lshl_add_u64 v[192:193], v[138:139], 0, s[4:5]
	v_lshl_add_u64 v[192:193], v[192:193], 0, vcc
	global_load_lds_dwordx4 v[192:193], off
	s_add_u32 m0, s14, 0xa000
	v_lshl_add_u64 v[192:193], v[138:139], 0, s[4:5]
	v_lshl_add_u64 v[192:193], v[192:193], 0, s[68:69]
	global_load_lds_dwordx4 v[192:193], off
	s_add_u32 m0, s14, 0xc000
	v_lshl_add_u64 v[192:193], v[138:139], 0, s[4:5]
	v_lshl_add_u64 v[192:193], v[192:193], 0, s[92:93]
	global_load_lds_dwordx4 v[192:193], off
	s_add_u32 m0, s14, 0xe000
	v_lshl_add_u64 v[192:193], v[138:139], 0, s[4:5]
	v_lshl_add_u64 v[192:193], v[192:193], 0, s[64:65]
	global_load_lds_dwordx4 v[192:193], off
	v_add3_u32 v192, s13, v145, v147
	v_add_u32_e32 v192, v192, v151
	ds_read_b128 v[192:195], v192
	s_waitcnt lgkmcnt(5)
	v_mfma_f32_32x32x16_bf16 v[82:97], v[196:199], v[154:157], v[82:97]
	v_mfma_f32_32x32x16_bf16 v[66:81], v[196:199], v[158:161], v[66:81]
	v_add3_u32 v196, s13, v145, v147
	v_add_u32_e32 v196, v196, v151
	ds_read_b128 v[196:199], v196 offset:4096
	s_waitcnt lgkmcnt(5)
	v_mfma_f32_32x32x16_bf16 v[50:65], v[200:203], v[154:157], v[50:65]
	v_mfma_f32_32x32x16_bf16 v[34:49], v[200:203], v[158:161], v[34:49]
	v_add3_u32 v200, s13, v145, v147
	v_add_u32_e32 v200, v200, v151
	ds_read_b128 v[200:203], v200 offset:8192
	s_waitcnt lgkmcnt(5)
	v_mfma_f32_32x32x16_bf16 v[18:33], v[204:207], v[154:157], v[18:33]
	v_mfma_f32_32x32x16_bf16 v[2:17], v[204:207], v[158:161], v[2:17]
	v_add3_u32 v204, s13, v145, v147
	v_add_u32_e32 v204, v204, v151
	ds_read_b128 v[204:207], v204 offset:12288
	v_add3_u32 v154, s13, v149, v147
	v_add_u32_e32 v154, v154, v152
	ds_read_b128 v[154:157], v154 offset:32768
	v_add3_u32 v158, s13, v149, v147
	v_add_u32_e32 v158, v158, v152
	ds_read_b128 v[158:161], v158 offset:36864
	s_waitcnt lgkmcnt(5)
	v_mfma_f32_32x32x16_bf16 v[114:129], v[192:195], v[162:165], v[114:129]
	v_mfma_f32_32x32x16_bf16 v[98:113], v[192:195], v[208:211], v[98:113]
	v_add3_u32 v192, s13, v145, v147
	v_add_u32_e32 v192, v192, v152
	ds_read_b128 v[192:195], v192
	s_waitcnt lgkmcnt(5)
	v_mfma_f32_32x32x16_bf16 v[82:97], v[196:199], v[162:165], v[82:97]
	v_mfma_f32_32x32x16_bf16 v[66:81], v[196:199], v[208:211], v[66:81]
	v_add3_u32 v196, s13, v145, v147
	v_add_u32_e32 v196, v196, v152
	ds_read_b128 v[196:199], v196 offset:4096
	s_waitcnt lgkmcnt(5)
	v_mfma_f32_32x32x16_bf16 v[50:65], v[200:203], v[162:165], v[50:65]
	v_mfma_f32_32x32x16_bf16 v[34:49], v[200:203], v[208:211], v[34:49]
	v_add3_u32 v200, s13, v145, v147
	v_add_u32_e32 v200, v200, v152
	ds_read_b128 v[200:203], v200 offset:8192
	s_waitcnt lgkmcnt(5)
	v_mfma_f32_32x32x16_bf16 v[18:33], v[204:207], v[162:165], v[18:33]
	v_mfma_f32_32x32x16_bf16 v[2:17], v[204:207], v[208:211], v[2:17]
	v_add3_u32 v204, s13, v145, v147
	v_add_u32_e32 v204, v204, v152
	ds_read_b128 v[204:207], v204 offset:12288
	v_add3_u32 v162, s13, v149, v147
	v_add_u32_e32 v162, v162, v153
	ds_read_b128 v[162:165], v162 offset:32768
	v_add3_u32 v208, s13, v149, v147
	v_add_u32_e32 v208, v208, v153
	ds_read_b128 v[208:211], v208 offset:36864
	s_waitcnt lgkmcnt(5)
	v_mfma_f32_32x32x16_bf16 v[114:129], v[192:195], v[154:157], v[114:129]
	v_mfma_f32_32x32x16_bf16 v[98:113], v[192:195], v[158:161], v[98:113]
	v_add3_u32 v192, s13, v145, v147
	v_add_u32_e32 v192, v192, v153
	ds_read_b128 v[192:195], v192
	s_waitcnt lgkmcnt(5)
	v_mfma_f32_32x32x16_bf16 v[82:97], v[196:199], v[154:157], v[82:97]
	v_mfma_f32_32x32x16_bf16 v[66:81], v[196:199], v[158:161], v[66:81]
	v_add3_u32 v196, s13, v145, v147
	v_add_u32_e32 v196, v196, v153
	ds_read_b128 v[196:199], v196 offset:4096
	s_waitcnt lgkmcnt(5)
	v_mfma_f32_32x32x16_bf16 v[50:65], v[200:203], v[154:157], v[50:65]
	v_mfma_f32_32x32x16_bf16 v[34:49], v[200:203], v[158:161], v[34:49]
	v_add3_u32 v200, s13, v145, v147
	v_add_u32_e32 v200, v200, v153
	ds_read_b128 v[200:203], v200 offset:8192
	s_waitcnt lgkmcnt(5)
	v_mfma_f32_32x32x16_bf16 v[18:33], v[204:207], v[154:157], v[18:33]
	v_mfma_f32_32x32x16_bf16 v[2:17], v[204:207], v[158:161], v[2:17]
	v_add3_u32 v204, s13, v145, v147
	v_add_u32_e32 v204, v204, v153
	ds_read_b128 v[204:207], v204 offset:12288
	s_waitcnt lgkmcnt(3)
	v_mfma_f32_32x32x16_bf16 v[114:129], v[192:195], v[162:165], v[114:129]
	v_mfma_f32_32x32x16_bf16 v[98:113], v[192:195], v[208:211], v[98:113]
	s_waitcnt lgkmcnt(2)
	v_mfma_f32_32x32x16_bf16 v[82:97], v[196:199], v[162:165], v[82:97]
	v_mfma_f32_32x32x16_bf16 v[66:81], v[196:199], v[208:211], v[66:81]
	s_waitcnt lgkmcnt(0)
	s_waitcnt vmcnt(0)
	s_barrier
; template <int EPI, int AMAP, int KOFFMODE, int K>
; __device__ __forceinline__ void gemm_phase(unsigned char* smem, const bf16_t* A, int lda, const bf16_t* Bt, int NT, const EpiArgs& ea) {
;     ...
;             fb[0][0] = *(const bf16x8*)(Bc + (((0) ^ yz) & 7) * 16);
;             fb[0][1] = *(const bf16x8*)(Bc + 32 * 128 + (((0) ^ yz) & 7) * 16);
; #pragma unroll
;             for (int i = 0; i < 4; ++i) fa[0][i] = *(const bf16x8*)(Ac + i * 32 * 128 + (((0) ^ yz) & 7) * 16);
; #pragma unroll
;             for (int s = 0; s < 4; ++s) {
;                 if (s < 3) {
;                     const int o_ = (((2 * (s + 1)) ^ yz) & 7) * 16;
;                     fb[(s + 1) & 1][0] = *(const bf16x8*)(Bc + o_);
;                     fb[(s + 1) & 1][1] = *(const bf16x8*)(Bc + 32 * 128 + o_);
; #pragma unroll
;                     for (int i = 0; i < 4; ++i) fa[(s + 1) & 1][i] = *(const bf16x8*)(Ac + i * 32 * 128 + o_);
;                 }
; #pragma unroll
;                 for (int i = 0; i < 4; ++i) {
;                     acc[i][0] = __builtin_amdgcn_mfma_f32_32x32x16_bf16(fa[s & 1][i], fb[s & 1][0], acc[i][0], 0, 0, 0);
;                     acc[i][1] = __builtin_amdgcn_mfma_f32_32x32x16_bf16(fa[s & 1][i], fb[s & 1][1], acc[i][1], 0, 0, 0);
;                 }
;                 __builtin_amdgcn_sched_barrier(0);
;             }
;             if (kt + 1 < nk) asm volatile("s_waitcnt vmcnt(0)" ::: "memory");
;             __builtin_amdgcn_s_barrier();
;             cur ^= 1;
;         }
;         gemm_epilogue<EPI>(smem + (cur ^ 1) * STGB, acc, m0, n0, wm, wn, lane, ea);
;         ++rr; u = un; have = have_next; m0 = m0n; n0 = n0n;
	v_add3_u32 v154, s12, v149, v147
	v_add_u32_e32 v154, v154, v150
	ds_read_b128 v[154:157], v154 offset:32768
	v_add3_u32 v158, s12, v149, v147
	v_add_u32_e32 v158, v158, v150
	ds_read_b128 v[158:161], v158 offset:36864
	v_add3_u32 v192, s12, v145, v147
	v_add_u32_e32 v192, v192, v150
	ds_read_b128 v[192:195], v192
	v_add3_u32 v196, s12, v145, v147
	v_add_u32_e32 v196, v196, v150
	ds_read_b128 v[196:199], v196 offset:4096
	v_mfma_f32_32x32x16_bf16 v[50:65], v[200:203], v[162:165], v[50:65]
	v_mfma_f32_32x32x16_bf16 v[34:49], v[200:203], v[208:211], v[34:49]
	v_add3_u32 v200, s12, v145, v147
	v_add_u32_e32 v200, v200, v150
	ds_read_b128 v[200:203], v200 offset:8192
	v_mfma_f32_32x32x16_bf16 v[18:33], v[204:207], v[162:165], v[18:33]
	v_mfma_f32_32x32x16_bf16 v[2:17], v[204:207], v[208:211], v[2:17]
	v_add3_u32 v204, s12, v145, v147
	v_add_u32_e32 v204, v204, v150
	ds_read_b128 v[204:207], v204 offset:12288
	s_xor_b32 s13, s9, 1
	s_add_u32 s4, s4, 0x80
	s_addc_u32 s5, s5, 0
	s_cmpk_eq_i32 s4, 0x780
	s_cbranch_scc0 .LBB0_155
	s_waitcnt lgkmcnt(0)
	s_andn2_b64 vcc, exec, s[2:3]
	s_lshl_b32 s2, s13, 16
	s_cbranch_vccnz .LBB0_147
	v_add_u32_e32 v136, s8, v141
	s_xor_b32 s3, s2, 0x10000
	v_ashrrev_i32_e32 v137, 31, v136
	v_add_u32_e32 v138, s7, v141
	v_add_u32_e32 v0, s3, v142
	v_lshlrev_b64 v[136:137], 11, v[136:137]
	v_ashrrev_i32_e32 v139, 31, v138
	v_add_u32_e32 v154, 0x8000, v0
	v_readfirstlane_b32 s3, v0
	v_lshlrev_b64 v[138:139], 11, v[138:139]
	v_lshl_add_u64 v[136:137], v[130:131], 0, v[136:137]
	s_mov_b32 m0, s3
	v_readfirstlane_b32 s3, v154
	v_add_u32_e32 v156, 0x2000, v0
	v_lshl_add_u64 v[138:139], v[132:133], 0, v[138:139]
	global_load_lds_dwordx4 v[136:137], off
	s_mov_b32 m0, s3
	s_mov_b64 s[4:5], 0x20000
	v_readfirstlane_b32 s3, v156
	v_add_u32_e32 v156, 0xa000, v0
	global_load_lds_dwordx4 v[138:139], off
	v_lshl_add_u64 v[154:155], v[136:137], 0, s[4:5]
	s_mov_b32 m0, s3
	v_readfirstlane_b32 s3, v156
	v_add_u32_e32 v156, 0x4000, v0
	global_load_lds_dwordx4 v[154:155], off
	v_lshl_add_u64 v[154:155], v[138:139], 0, s[4:5]
	s_mov_b32 m0, s3
	s_mov_b64 s[4:5], 0x40000
	v_readfirstlane_b32 s3, v156
	v_add_u32_e32 v156, 0xc000, v0
	global_load_lds_dwordx4 v[154:155], off
	v_lshl_add_u64 v[154:155], v[136:137], 0, s[4:5]
	s_mov_b32 m0, s3
	v_readfirstlane_b32 s3, v156
	global_load_lds_dwordx4 v[154:155], off
	v_lshl_add_u64 v[154:155], v[138:139], 0, s[4:5]
	s_mov_b32 m0, s3
	s_mov_b64 s[4:5], 0x60000
	global_load_lds_dwordx4 v[154:155], off
	v_add_u32_e32 v154, 0x6000, v0
	v_add_u32_e32 v0, 0xe000, v0
	v_readfirstlane_b32 s3, v154
	v_lshl_add_u64 v[136:137], v[136:137], 0, s[4:5]
	s_mov_b32 m0, s3
	v_readfirstlane_b32 s3, v0
	global_load_lds_dwordx4 v[136:137], off
	v_lshl_add_u64 v[136:137], v[138:139], 0, s[4:5]
	s_mov_b32 m0, s3
	s_nop 0
	global_load_lds_dwordx4 v[136:137], off
	s_branch .LBB0_147

; template <int EPI, int AMAP, int KOFFMODE, int K>
; __device__ __forceinline__ void gemm_phase(unsigned char* smem, const bf16_t* A, int lda, const bf16_t* Bt, int NT, const EpiArgs& ea) {
;     ...
;         for (int kt = 0; kt < nk; ++kt) {
;             if (kt + 1 < nk) GEMM_DMA(m0, n0, kt + 1, cur ^ 1);
;             else if (have_next) GEMM_DMA(m0n, n0n, 0, cur ^ 1);
;             const unsigned char* Ac = smem + cur * STGB + (wm * 128 + l31) * 128;
;             const unsigned char* Bc = smem + cur * STGB + 32768 + (wn * 64 + l31) * 128;
;             bf16x8 fa[2][4], fb[2][2];
;             fb[0][0] = *(const bf16x8*)(Bc + (((0) ^ yz) & 7) * 16);
;             fb[0][1] = *(const bf16x8*)(Bc + 32 * 128 + (((0) ^ yz) & 7) * 16);
; #pragma unroll
;             for (int i = 0; i < 4; ++i) fa[0][i] = *(const bf16x8*)(Ac + i * 32 * 128 + (((0) ^ yz) & 7) * 16);
; #pragma unroll
;             for (int s = 0; s < 4; ++s) {
;                 if (s < 3) {
;                     const int o_ = (((2 * (s + 1)) ^ yz) & 7) * 16;
;                     fb[(s + 1) & 1][0] = *(const bf16x8*)(Bc + o_);
;                     fb[(s + 1) & 1][1] = *(const bf16x8*)(Bc + 32 * 128 + o_);
; #pragma unroll
;                     for (int i = 0; i < 4; ++i) fa[(s + 1) & 1][i] = *(const bf16x8*)(Ac + i * 32 * 128 + o_);
;                 }
; #pragma unroll
;                 for (int i = 0; i < 4; ++i) {
;                     acc[i][0] = __builtin_amdgcn_mfma_f32_32x32x16_bf16(fa[s & 1][i], fb[s & 1][0], acc[i][0], 0, 0, 0);
;                     acc[i][1] = __builtin_amdgcn_mfma_f32_32x32x16_bf16(fa[s & 1][i], fb[s & 1][1], acc[i][1], 0, 0, 0);
;                 }
;                 __builtin_amdgcn_sched_barrier(0);
;             }
;             if (kt + 1 < nk) asm volatile("s_waitcnt vmcnt(0)" ::: "memory");
;             __builtin_amdgcn_s_barrier();
.LBB0_520:
	s_mov_b32 s9, s13
	s_lshl_b32 s13, s9, 16
	s_xor_b32 s12, s13, 0x10000
	v_readfirstlane_b32 s14, v142
	s_nop 0
	s_add_u32 s14, s14, s12
	v_add3_u32 v162, s13, v149, v147
	v_add_u32_e32 v162, v162, v151
	ds_read_b128 v[162:165], v162 offset:32768
	v_add3_u32 v208, s13, v149, v147
	v_add_u32_e32 v208, v208, v151
	ds_read_b128 v[208:211], v208 offset:36864
	s_waitcnt lgkmcnt(5)
	v_mfma_f32_32x32x16_bf16 v[114:129], v[192:195], v[154:157], v[114:129]
	v_mfma_f32_32x32x16_bf16 v[82:97], v[192:195], v[158:161], v[82:97]
	s_mov_b32 m0, s14
	v_lshl_add_u64 v[192:193], v[136:137], 0, s[4:5]
	v_lshl_add_u64 v[192:193], v[192:193], 0, s[20:21]
	global_load_lds_dwordx4 v[192:193], off
	s_add_u32 m0, s14, 0x2000
	v_lshl_add_u64 v[192:193], v[136:137], 0, s[4:5]
	v_lshl_add_u64 v[192:193], v[192:193], 0, s[80:81]
	global_load_lds_dwordx4 v[192:193], off
	s_add_u32 m0, s14, 0x4000
	v_lshl_add_u64 v[192:193], v[136:137], 0, s[4:5]
	v_lshl_add_u64 v[192:193], v[192:193], 0, s[88:89]
	global_load_lds_dwordx4 v[192:193], off
	s_add_u32 m0, s14, 0x6000
	v_lshl_add_u64 v[192:193], v[136:137], 0, s[4:5]
	v_lshl_add_u64 v[192:193], v[192:193], 0, s[62:63]
	global_load_lds_dwordx4 v[192:193], off
	s_add_u32 m0, s14, 0x8000
	v_lshl_add_u64 v[192:193], v[138:139], 0, s[4:5]
	v_lshl_add_u64 v[192:193], v[192:193], 0, vcc
	global_load_lds_dwordx4 v[192:193], off
	s_add_u32 m0, s14, 0xa000
	v_lshl_add_u64 v[192:193], v[138:139], 0, s[4:5]
	v_lshl_add_u64 v[192:193], v[192:193], 0, s[68:69]
	global_load_lds_dwordx4 v[192:193], off
	s_add_u32 m0, s14, 0xc000
	v_lshl_add_u64 v[192:193], v[138:139], 0, s[4:5]
	v_lshl_add_u64 v[192:193], v[192:193], 0, s[92:93]
	global_load_lds_dwordx4 v[192:193], off
	s_add_u32 m0, s14, 0xe000
	v_lshl_add_u64 v[192:193], v[138:139], 0, s[4:5]
	v_lshl_add_u64 v[192:193], v[192:193], 0, s[64:65]
	global_load_lds_dwordx4 v[192:193], off
	v_add3_u32 v192, s13, v145, v147
	v_add_u32_e32 v192, v192, v151
	ds_read_b128 v[192:195], v192
	s_waitcnt lgkmcnt(5)
	v_mfma_f32_32x32x16_bf16 v[98:113], v[196:199], v[154:157], v[98:113]
	v_mfma_f32_32x32x16_bf16 v[66:81], v[196:199], v[158:161], v[66:81]
	v_add3_u32 v196, s13, v145, v147
	v_add_u32_e32 v196, v196, v151
	ds_read_b128 v[196:199], v196 offset:4096
	s_waitcnt lgkmcnt(5)
	v_mfma_f32_32x32x16_bf16 v[50:65], v[200:203], v[154:157], v[50:65]
	v_mfma_f32_32x32x16_bf16 v[18:33], v[200:203], v[158:161], v[18:33]
	v_add3_u32 v200, s13, v145, v147
	v_add_u32_e32 v200, v200, v151
	ds_read_b128 v[200:203], v200 offset:8192
	s_waitcnt lgkmcnt(5)
	v_mfma_f32_32x32x16_bf16 v[34:49], v[204:207], v[154:157], v[34:49]
	v_mfma_f32_32x32x16_bf16 v[2:17], v[204:207], v[158:161], v[2:17]
	v_add3_u32 v204, s13, v145, v147
	v_add_u32_e32 v204, v204, v151
	ds_read_b128 v[204:207], v204 offset:12288
	v_add3_u32 v154, s13, v149, v147
	v_add_u32_e32 v154, v154, v152
	ds_read_b128 v[154:157], v154 offset:32768
	v_add3_u32 v158, s13, v149, v147
	v_add_u32_e32 v158, v158, v152
	ds_read_b128 v[158:161], v158 offset:36864
	s_waitcnt lgkmcnt(5)
	v_mfma_f32_32x32x16_bf16 v[114:129], v[192:195], v[162:165], v[114:129]
	v_mfma_f32_32x32x16_bf16 v[82:97], v[192:195], v[208:211], v[82:97]
	v_add3_u32 v192, s13, v145, v147
	v_add_u32_e32 v192, v192, v152
	ds_read_b128 v[192:195], v192
	s_waitcnt lgkmcnt(5)
	v_mfma_f32_32x32x16_bf16 v[98:113], v[196:199], v[162:165], v[98:113]
	v_mfma_f32_32x32x16_bf16 v[66:81], v[196:199], v[208:211], v[66:81]
	v_add3_u32 v196, s13, v145, v147
	v_add_u32_e32 v196, v196, v152
	ds_read_b128 v[196:199], v196 offset:4096
	s_waitcnt lgkmcnt(5)
	v_mfma_f32_32x32x16_bf16 v[50:65], v[200:203], v[162:165], v[50:65]
	v_mfma_f32_32x32x16_bf16 v[18:33], v[200:203], v[208:211], v[18:33]
	v_add3_u32 v200, s13, v145, v147
	v_add_u32_e32 v200, v200, v152
	ds_read_b128 v[200:203], v200 offset:8192
	s_waitcnt lgkmcnt(5)
	v_mfma_f32_32x32x16_bf16 v[34:49], v[204:207], v[162:165], v[34:49]
	v_mfma_f32_32x32x16_bf16 v[2:17], v[204:207], v[208:211], v[2:17]
	v_add3_u32 v204, s13, v145, v147
	v_add_u32_e32 v204, v204, v152
	ds_read_b128 v[204:207], v204 offset:12288
	v_add3_u32 v162, s13, v149, v147
	v_add_u32_e32 v162, v162, v153
	ds_read_b128 v[162:165], v162 offset:32768
	v_add3_u32 v208, s13, v149, v147
	v_add_u32_e32 v208, v208, v153
	ds_read_b128 v[208:211], v208 offset:36864
	s_waitcnt lgkmcnt(5)
	v_mfma_f32_32x32x16_bf16 v[114:129], v[192:195], v[154:157], v[114:129]
	v_mfma_f32_32x32x16_bf16 v[82:97], v[192:195], v[158:161], v[82:97]
	v_add3_u32 v192, s13, v145, v147
	v_add_u32_e32 v192, v192, v153
	ds_read_b128 v[192:195], v192
	s_waitcnt lgkmcnt(5)
	v_mfma_f32_32x32x16_bf16 v[98:113], v[196:199], v[154:157], v[98:113]
	v_mfma_f32_32x32x16_bf16 v[66:81], v[196:199], v[158:161], v[66:81]
	v_add3_u32 v196, s13, v145, v147
	v_add_u32_e32 v196, v196, v153
	ds_read_b128 v[196:199], v196 offset:4096
	s_waitcnt lgkmcnt(5)
	v_mfma_f32_32x32x16_bf16 v[50:65], v[200:203], v[154:157], v[50:65]
	v_mfma_f32_32x32x16_bf16 v[18:33], v[200:203], v[158:161], v[18:33]
	v_add3_u32 v200, s13, v145, v147
	v_add_u32_e32 v200, v200, v153
	ds_read_b128 v[200:203], v200 offset:8192
	s_waitcnt lgkmcnt(5)
	v_mfma_f32_32x32x16_bf16 v[34:49], v[204:207], v[154:157], v[34:49]
	v_mfma_f32_32x32x16_bf16 v[2:17], v[204:207], v[158:161], v[2:17]
	v_add3_u32 v204, s13, v145, v147
	v_add_u32_e32 v204, v204, v153
	ds_read_b128 v[204:207], v204 offset:12288
	s_waitcnt lgkmcnt(3)
	v_mfma_f32_32x32x16_bf16 v[114:129], v[192:195], v[162:165], v[114:129]
	v_mfma_f32_32x32x16_bf16 v[82:97], v[192:195], v[208:211], v[82:97]
	s_waitcnt lgkmcnt(2)
	v_mfma_f32_32x32x16_bf16 v[98:113], v[196:199], v[162:165], v[98:113]
	v_mfma_f32_32x32x16_bf16 v[66:81], v[196:199], v[208:211], v[66:81]
	s_waitcnt lgkmcnt(0)
	s_waitcnt vmcnt(0)
	s_barrier
; template <int EPI, int AMAP, int KOFFMODE, int K>
; __device__ __forceinline__ void gemm_phase(unsigned char* smem, const bf16_t* A, int lda, const bf16_t* Bt, int NT, const EpiArgs& ea) {
;     ...
;             fb[0][0] = *(const bf16x8*)(Bc + (((0) ^ yz) & 7) * 16);
;             fb[0][1] = *(const bf16x8*)(Bc + 32 * 128 + (((0) ^ yz) & 7) * 16);
; #pragma unroll
;             for (int i = 0; i < 4; ++i) fa[0][i] = *(const bf16x8*)(Ac + i * 32 * 128 + (((0) ^ yz) & 7) * 16);
; #pragma unroll
;             for (int s = 0; s < 4; ++s) {
;                 if (s < 3) {
;                     const int o_ = (((2 * (s + 1)) ^ yz) & 7) * 16;
;                     fb[(s + 1) & 1][0] = *(const bf16x8*)(Bc + o_);
;                     fb[(s + 1) & 1][1] = *(const bf16x8*)(Bc + 32 * 128 + o_);
; #pragma unroll
;                     for (int i = 0; i < 4; ++i) fa[(s + 1) & 1][i] = *(const bf16x8*)(Ac + i * 32 * 128 + o_);
;                 }
; #pragma unroll
;                 for (int i = 0; i < 4; ++i) {
;                     acc[i][0] = __builtin_amdgcn_mfma_f32_32x32x16_bf16(fa[s & 1][i], fb[s & 1][0], acc[i][0], 0, 0, 0);
;                     acc[i][1] = __builtin_amdgcn_mfma_f32_32x32x16_bf16(fa[s & 1][i], fb[s & 1][1], acc[i][1], 0, 0, 0);
;                 }
;                 __builtin_amdgcn_sched_barrier(0);
;             }
;             if (kt + 1 < nk) asm volatile("s_waitcnt vmcnt(0)" ::: "memory");
;             __builtin_amdgcn_s_barrier();
;             cur ^= 1;
;         }
;         gemm_epilogue<EPI>(smem + (cur ^ 1) * STGB, acc, m0, n0, wm, wn, lane, ea);
;         ++rr; u = un; have = have_next; m0 = m0n; n0 = n0n;
	v_add3_u32 v154, s12, v149, v147
	v_add_u32_e32 v154, v154, v150
	ds_read_b128 v[154:157], v154 offset:32768
	v_add3_u32 v158, s12, v149, v147
	v_add_u32_e32 v158, v158, v150
	ds_read_b128 v[158:161], v158 offset:36864
	v_add3_u32 v192, s12, v145, v147
	v_add_u32_e32 v192, v192, v150
	ds_read_b128 v[192:195], v192
	v_add3_u32 v196, s12, v145, v147
	v_add_u32_e32 v196, v196, v150
	ds_read_b128 v[196:199], v196 offset:4096
	v_mfma_f32_32x32x16_bf16 v[50:65], v[200:203], v[162:165], v[50:65]
	v_mfma_f32_32x32x16_bf16 v[18:33], v[200:203], v[208:211], v[18:33]
	v_add3_u32 v200, s12, v145, v147
	v_add_u32_e32 v200, v200, v150
	ds_read_b128 v[200:203], v200 offset:8192
	v_mfma_f32_32x32x16_bf16 v[34:49], v[204:207], v[162:165], v[34:49]
	v_mfma_f32_32x32x16_bf16 v[2:17], v[204:207], v[208:211], v[2:17]
	v_add3_u32 v204, s12, v145, v147
	v_add_u32_e32 v204, v204, v150
	ds_read_b128 v[204:207], v204 offset:12288
	s_xor_b32 s13, s9, 1
	s_add_u32 s4, s4, 0x80
	s_addc_u32 s5, s5, 0
	s_cmpk_eq_i32 s4, 0x780
	s_cbranch_scc0 .LBB0_520
	s_waitcnt lgkmcnt(0)
	s_andn2_b64 vcc, exec, s[2:3]
	s_lshl_b32 s2, s13, 16
	s_mov_b64 s[62:63], 0x80
	s_mov_b64 s[64:65], 0x10000
	s_mov_b32 s92, 0x3e38aa3b
	s_cbranch_vccnz .LBB0_523
	v_add_u32_e32 v136, s8, v141
	s_xor_b32 s3, s2, 0x10000
	v_ashrrev_i32_e32 v137, 31, v136
	v_add_u32_e32 v138, s7, v141
	v_add_u32_e32 v0, s3, v142
	v_lshlrev_b64 v[136:137], 11, v[136:137]
	v_ashrrev_i32_e32 v139, 31, v138
	v_add_u32_e32 v154, 0x8000, v0
	v_readfirstlane_b32 s3, v0
	v_lshlrev_b64 v[138:139], 11, v[138:139]
	v_lshl_add_u64 v[136:137], v[130:131], 0, v[136:137]
	s_mov_b32 m0, s3
	v_readfirstlane_b32 s3, v154
	v_add_u32_e32 v156, 0x2000, v0
	v_lshl_add_u64 v[138:139], v[132:133], 0, v[138:139]
	global_load_lds_dwordx4 v[136:137], off
	s_mov_b32 m0, s3
	s_mov_b64 s[4:5], 0x20000
	v_readfirstlane_b32 s3, v156
	v_add_u32_e32 v156, 0xa000, v0
	global_load_lds_dwordx4 v[138:139], off
	v_lshl_add_u64 v[154:155], v[136:137], 0, s[4:5]
	s_mov_b32 m0, s3
	v_readfirstlane_b32 s3, v156
	v_add_u32_e32 v156, 0x4000, v0
	global_load_lds_dwordx4 v[154:155], off
	v_lshl_add_u64 v[154:155], v[138:139], 0, s[4:5]
	s_mov_b32 m0, s3
	s_mov_b64 s[4:5], 0x40000
	v_readfirstlane_b32 s3, v156
	v_add_u32_e32 v156, 0xc000, v0
	global_load_lds_dwordx4 v[154:155], off
	v_lshl_add_u64 v[154:155], v[136:137], 0, s[4:5]
	s_mov_b32 m0, s3
	v_readfirstlane_b32 s3, v156
	global_load_lds_dwordx4 v[154:155], off
	v_lshl_add_u64 v[154:155], v[138:139], 0, s[4:5]
	s_mov_b32 m0, s3
	s_mov_b64 s[4:5], 0x60000
	global_load_lds_dwordx4 v[154:155], off
	v_add_u32_e32 v154, 0x6000, v0
	v_add_u32_e32 v0, 0xe000, v0
	v_readfirstlane_b32 s3, v154
	v_lshl_add_u64 v[136:137], v[136:137], 0, s[4:5]
	s_mov_b32 m0, s3
	v_readfirstlane_b32 s3, v0
	global_load_lds_dwordx4 v[136:137], off
	v_lshl_add_u64 v[136:137], v[138:139], 0, s[4:5]
	s_mov_b32 m0, s3
	s_nop 0
	global_load_lds_dwordx4 v[136:137], off
